# F with 8 bytes of entry padding (code placement check)
# baseline (speedup 1.0000x reference)
; #define LAS __attribute__((address_space(3)))
; __global__ void __launch_bounds__(NTHR, 2) fwd_megakernel(Args args) {
;     extern __shared__ __attribute__((aligned(16))) unsigned char lds_raw[];
;     LAS unsigned char* lds = (LAS unsigned char*)lds_raw;
;     cg::grid_group grid = cg::this_grid();
;     if (gridDim.x == 0x7fffffffu) grid.sync();
;     { volatile LAS unsigned* mz = (volatile LAS unsigned*)(lds + LDS_BYTES - 64); if (threadIdx.x < 16) mz[threadIdx.x] = 0u; }
_Z14fwd_megakernel4Args:
	s_nop 0
	s_nop 0
	s_load_dwordx2 s[6:7], s[0:1], 0x90
	s_load_dwordx16 s[68:83], s[0:1], 0x0
	s_load_dwordx16 s[52:67], s[0:1], 0x40
	s_add_u32 s8, s0, 0x90
	s_addc_u32 s9, s1, 0
	s_waitcnt lgkmcnt(0)
	s_cmp_eq_u32 s6, 0x7fffffff
	s_cbranch_scc1 .LBB0_2
	v_and_b32_e32 v216, 0x3ff, v0
	s_load_dword s3, s[0:1], 0x98
	s_cbranch_execz .LBB0_3
	s_branch .LBB0_14
